# seam prefetch with the dummy LDS-DMA target moved to the unused 15 KiB phase-scratch area (no overlap with the GEMM ring)
# speedup vs baseline: 1.0011x; 1.0011x over previous
.Lseam_pf5:
	s_mov_b64 exec, s[10:11]
	v_readlane_b32 s78, v254, 20
	v_mov_b32_e32 v2, s78
	ds_read_b64 v[2:3], v2
	v_mbcnt_lo_u32_b32 v4, -1, 0
	v_mbcnt_hi_u32_b32 v4, -1, v4
	v_readlane_b32 s79, v252, 2
	v_readlane_b32 s82, v252, 8
	v_readlane_b32 s83, v254, 36
	s_waitcnt lgkmcnt(0)
	v_readfirstlane_b32 s80, v2
	v_readfirstlane_b32 s81, v3
	s_and_b32 s84, s79, 1
	s_lshl_b32 s84, s84, 2
	s_lshr_b32 s85, s79, 6
	s_add_i32 s84, s84, s85
	s_lshr_b32 s82, s82, 6
	s_add_i32 s82, s82, -1
	s_lshl_b32 s85, s82, 8
	s_add_i32 s85, s85, 0x21000
	s_mov_b32 m0, s85
	s_mul_i32 s86, s83, 0xc00000
	s_mul_i32 s87, s84, 0x180000
	s_add_u32 s86, s86, s87
	s_add_u32 s86, s86, 0x76e00000
	s_add_u32 s86, s80, s86
	s_addc_u32 s87, s81, 0
	v_lshrrev_b32_e32 v5, 1, v4
	v_lshl_add_u32 v5, s82, 5, v5
	v_mul_u32_u24_e32 v5, 0x1800, v5
	v_and_b32_e32 v6, 1, v4
	v_lshl_add_u32 v5, v6, 7, v5
	global_load_lds_dword v5, s[86:87]
	s_and_b32 s86, s79, 7
	s_lshr_b32 s86, s86, 1
	s_lshl_b32 s86, s86, 3
	s_bfe_u32 s87, s79, 0x30003
	s_add_i32 s86, s86, s87
	s_lshl_b32 s86, s86, 17
	s_add_i32 s87, s84, 60
	s_lshl_b32 s87, s87, 22
	s_add_u32 s86, s86, s87
	s_add_u32 s86, s86, 0x36d00000
	s_add_u32 s86, s80, s86
	s_addc_u32 s87, s81, 0
	v_lshlrev_b32_e32 v5, 7, v4
	s_lshl_b32 s85, s82, 1
	s_add_i32 s85, s85, 0
	s_lshr_b32 s79, s85, 3
	s_lshl_b32 s79, s79, 25
	s_and_b32 s85, s85, 7
	s_lshl_b32 s85, s85, 13
	s_add_i32 s85, s85, s79
	v_add_u32_e32 v6, s85, v5
	global_load_lds_dword v6, s[86:87]
	s_lshl_b32 s85, s82, 1
	s_add_i32 s85, s85, 1
	s_lshr_b32 s79, s85, 3
	s_lshl_b32 s79, s79, 25
	s_and_b32 s85, s85, 7
	s_lshl_b32 s85, s85, 13
	s_add_i32 s85, s85, s79
	v_add_u32_e32 v6, s85, v5
	global_load_lds_dword v6, s[86:87]
	s_branch .LBB0_566

.Lseam_pf6:
	s_mov_b64 exec, s[10:11]
	v_readlane_b32 s78, v254, 20
	v_mov_b32_e32 v2, s78
	ds_read_b64 v[2:3], v2
	v_mbcnt_lo_u32_b32 v4, -1, 0
	v_mbcnt_hi_u32_b32 v4, -1, v4
	v_readlane_b32 s79, v252, 2
	v_readlane_b32 s82, v252, 8
	v_readlane_b32 s83, v254, 36
	s_waitcnt lgkmcnt(0)
	v_readfirstlane_b32 s80, v2
	v_readfirstlane_b32 s81, v3
	s_and_b32 s84, s79, 1
	s_lshl_b32 s84, s84, 2
	s_lshr_b32 s85, s79, 6
	s_add_i32 s84, s84, s85
	s_lshr_b32 s82, s82, 6
	s_add_i32 s82, s82, -1
	s_lshl_b32 s85, s82, 8
	s_add_i32 s85, s85, 0x21000
	s_mov_b32 m0, s85
	s_mul_i32 s86, s83, 0x800000
	s_mul_i32 s87, s84, 0x100000
	s_add_u32 s86, s86, s87
	s_add_u32 s86, s86, 0x16500000
	s_add_u32 s86, s80, s86
	s_addc_u32 s87, s81, 0
	v_lshrrev_b32_e32 v5, 1, v4
	v_lshl_add_u32 v5, s82, 5, v5
	v_mul_u32_u24_e32 v5, 0x1000, v5
	v_and_b32_e32 v6, 1, v4
	v_lshl_add_u32 v5, v6, 7, v5
	global_load_lds_dword v5, s[86:87]
	s_branch .LBB0_643
